# masked-score path of banded attention: 16 LUT gathers issued together instead of serialised (on top of MLA body + phase-0 rotation)
# baseline (speedup 1.0000x reference)
.LBB0_510:
	s_andn2_b64 vcc, exec, s[4:5]
	s_cbranch_vccnz .LBB0_544
	v_add_u32_e32 v138, s35, v133
	v_add_u32_e32 v200, 0xffffff80, v138
	v_add_u32_e32 v139, s35, v131
	s_cmp_gt_i32 s14, -1
	v_cmp_gt_u32_e32 vcc, s97, v139
	v_cmp_gt_i32_e64 s[4:5], s33, v200
	s_cselect_b64 s[14:15], -1, 0
	s_and_b64 s[4:5], s[4:5], vcc
	s_and_b64 s[38:39], s[14:15], s[4:5]
	v_mov_b32_e32 v185, 0xff800000
	v_mov_b32_e32 v184, 0xff800000
	s_and_saveexec_b64 s[4:5], s[38:39]
	s_cbranch_execz .LBB0_513
	v_add_u32_e32 v184, 0, v132
	ds_read_b32 v184, v184
.LBB0_513:
	s_or_b64 exec, exec, s[4:5]
	v_add_u32_e32 v201, 0xffffff81, v138
	v_add_u32_e32 v202, 1, v139
	v_cmp_gt_u32_e32 vcc, s97, v202
	v_cmp_gt_i32_e64 s[4:5], s33, v201
	s_and_b64 s[4:5], s[4:5], vcc
	s_and_b64 s[38:39], s[14:15], s[4:5]
	s_and_saveexec_b64 s[4:5], s[38:39]
	s_cbranch_execz .LBB0_515
	v_add_u32_e32 v185, 0, v130
	v_add_u32_e32 v185, 0x1c004, v185
	ds_read_b32 v185, v185
.LBB0_515:
	s_or_b64 exec, exec, s[4:5]
	v_add_u32_e32 v203, 0xffffff82, v138
	v_add_u32_e32 v204, 2, v139
	v_cmp_gt_u32_e32 vcc, s97, v204
	v_cmp_gt_i32_e64 s[4:5], s33, v203
	s_and_b64 s[4:5], s[4:5], vcc
	s_and_b64 s[38:39], s[14:15], s[4:5]
	v_mov_b32_e32 v187, 0xff800000
	v_mov_b32_e32 v186, 0xff800000
	s_and_saveexec_b64 s[4:5], s[38:39]
	s_cbranch_execz .LBB0_517
	v_add_u32_e32 v186, 0, v130
	v_add_u32_e32 v186, 0x1c008, v186
	ds_read_b32 v186, v186
.LBB0_517:
	s_or_b64 exec, exec, s[4:5]
	v_add_u32_e32 v205, 0xffffff83, v138
	v_add_u32_e32 v206, 3, v139
	v_cmp_gt_u32_e32 vcc, s97, v206
	v_cmp_gt_i32_e64 s[4:5], s33, v205
	s_and_b64 s[4:5], s[4:5], vcc
	s_and_b64 s[38:39], s[14:15], s[4:5]
	s_and_saveexec_b64 s[4:5], s[38:39]
	s_cbranch_execz .LBB0_519
	v_add_u32_e32 v187, 0, v130
	v_add_u32_e32 v187, 0x1c00c, v187
	ds_read_b32 v187, v187
.LBB0_519:
	s_or_b64 exec, exec, s[4:5]
	v_add_u32_e32 v207, 0xffffff88, v138
	v_add_u32_e32 v208, 8, v139
	v_cmp_gt_u32_e32 vcc, s97, v208
	v_cmp_gt_i32_e64 s[4:5], s33, v207
	s_and_b64 s[4:5], s[4:5], vcc
	s_and_b64 s[38:39], s[14:15], s[4:5]
	v_mov_b32_e32 v189, 0xff800000
	v_mov_b32_e32 v188, 0xff800000
	s_and_saveexec_b64 s[4:5], s[38:39]
	s_cbranch_execz .LBB0_521
	v_add_u32_e32 v188, 0, v130
	v_add_u32_e32 v188, 0x1c020, v188
	ds_read_b32 v188, v188
.LBB0_521:
	s_or_b64 exec, exec, s[4:5]
	v_add_u32_e32 v209, 0xffffff89, v138
	v_add_u32_e32 v210, 9, v139
	v_cmp_gt_u32_e32 vcc, s97, v210
	v_cmp_gt_i32_e64 s[4:5], s33, v209
	s_and_b64 s[4:5], s[4:5], vcc
	s_and_b64 s[38:39], s[14:15], s[4:5]
	s_and_saveexec_b64 s[4:5], s[38:39]
	s_cbranch_execz .LBB0_523
	v_add_u32_e32 v189, 0, v130
	v_add_u32_e32 v189, 0x1c024, v189
	ds_read_b32 v189, v189
.LBB0_523:
	s_or_b64 exec, exec, s[4:5]
	v_add_u32_e32 v211, 0xffffff8a, v138
	v_add_u32_e32 v212, 10, v139
	v_cmp_gt_u32_e32 vcc, s97, v212
	v_cmp_gt_i32_e64 s[4:5], s33, v211
	s_and_b64 s[4:5], s[4:5], vcc
	s_and_b64 s[38:39], s[14:15], s[4:5]
	v_mov_b32_e32 v191, 0xff800000
	v_mov_b32_e32 v190, 0xff800000
	s_and_saveexec_b64 s[4:5], s[38:39]
	s_cbranch_execz .LBB0_525
	v_add_u32_e32 v190, 0, v130
	v_add_u32_e32 v190, 0x1c028, v190
	ds_read_b32 v190, v190
.LBB0_525:
	s_or_b64 exec, exec, s[4:5]
	v_add_u32_e32 v213, 0xffffff8b, v138
	v_add_u32_e32 v214, 11, v139
	v_cmp_gt_u32_e32 vcc, s97, v214
	v_cmp_gt_i32_e64 s[4:5], s33, v213
	s_and_b64 s[4:5], s[4:5], vcc
	s_and_b64 s[38:39], s[14:15], s[4:5]
	s_and_saveexec_b64 s[4:5], s[38:39]
	s_cbranch_execz .LBB0_527
	v_add_u32_e32 v191, 0, v130
	v_add_u32_e32 v191, 0x1c02c, v191
	ds_read_b32 v191, v191
.LBB0_527:
	s_or_b64 exec, exec, s[4:5]
	v_add_u32_e32 v215, 0xffffff90, v138
	v_add_u32_e32 v216, 16, v139
	v_cmp_gt_u32_e32 vcc, s97, v216
	v_cmp_gt_i32_e64 s[4:5], s33, v215
	s_and_b64 s[4:5], s[4:5], vcc
	s_and_b64 s[38:39], s[14:15], s[4:5]
	v_mov_b32_e32 v193, 0xff800000
	v_mov_b32_e32 v192, 0xff800000
	s_and_saveexec_b64 s[4:5], s[38:39]
	s_cbranch_execz .LBB0_529
	v_add_u32_e32 v192, 0, v130
	v_add_u32_e32 v192, 0x1c040, v192
	ds_read_b32 v192, v192
.LBB0_529:
	s_or_b64 exec, exec, s[4:5]
	v_add_u32_e32 v217, 0xffffff91, v138
	v_add_u32_e32 v218, 17, v139
	v_cmp_gt_u32_e32 vcc, s97, v218
	v_cmp_gt_i32_e64 s[4:5], s33, v217
	s_and_b64 s[4:5], s[4:5], vcc
	s_and_b64 s[38:39], s[14:15], s[4:5]
	s_and_saveexec_b64 s[4:5], s[38:39]
	s_cbranch_execz .LBB0_531
	v_add_u32_e32 v193, 0, v130
	v_add_u32_e32 v193, 0x1c044, v193
	ds_read_b32 v193, v193
.LBB0_531:
	s_or_b64 exec, exec, s[4:5]
	v_add_u32_e32 v219, 0xffffff92, v138
	v_add_u32_e32 v220, 18, v139
	v_cmp_gt_u32_e32 vcc, s97, v220
	v_cmp_gt_i32_e64 s[4:5], s33, v219
	s_and_b64 s[4:5], s[4:5], vcc
	s_and_b64 s[38:39], s[14:15], s[4:5]
	v_mov_b32_e32 v195, 0xff800000
	v_mov_b32_e32 v194, 0xff800000
	s_and_saveexec_b64 s[4:5], s[38:39]
	s_cbranch_execz .LBB0_533
	v_add_u32_e32 v194, 0, v130
	v_add_u32_e32 v194, 0x1c048, v194
	ds_read_b32 v194, v194
.LBB0_533:
	s_or_b64 exec, exec, s[4:5]
	v_add_u32_e32 v221, 0xffffff93, v138
	v_add_u32_e32 v222, 19, v139
	v_cmp_gt_u32_e32 vcc, s97, v222
	v_cmp_gt_i32_e64 s[4:5], s33, v221
	s_and_b64 s[4:5], s[4:5], vcc
	s_and_b64 s[38:39], s[14:15], s[4:5]
	s_and_saveexec_b64 s[4:5], s[38:39]
	s_cbranch_execz .LBB0_535
	v_add_u32_e32 v195, 0, v130
	v_add_u32_e32 v195, 0x1c04c, v195
	ds_read_b32 v195, v195
.LBB0_535:
	s_or_b64 exec, exec, s[4:5]
	v_add_u32_e32 v223, 0xffffff98, v138
	v_add_u32_e32 v224, 24, v139
	v_cmp_gt_u32_e32 vcc, s97, v224
	v_cmp_gt_i32_e64 s[4:5], s33, v223
	s_and_b64 s[4:5], s[4:5], vcc
	s_and_b64 s[38:39], s[14:15], s[4:5]
	v_mov_b32_e32 v197, 0xff800000
	v_mov_b32_e32 v196, 0xff800000
	s_and_saveexec_b64 s[4:5], s[38:39]
	s_cbranch_execz .LBB0_537
	v_add_u32_e32 v196, 0, v130
	v_add_u32_e32 v196, 0x1c060, v196
	ds_read_b32 v196, v196
.LBB0_537:
	s_or_b64 exec, exec, s[4:5]
	v_add_u32_e32 v225, 0xffffff99, v138
	v_add_u32_e32 v226, 25, v139
	v_cmp_gt_u32_e32 vcc, s97, v226
	v_cmp_gt_i32_e64 s[4:5], s33, v225
	s_and_b64 s[4:5], s[4:5], vcc
	s_and_b64 s[38:39], s[14:15], s[4:5]
	s_and_saveexec_b64 s[4:5], s[38:39]
	s_cbranch_execz .LBB0_539
	v_add_u32_e32 v197, 0, v130
	v_add_u32_e32 v197, 0x1c064, v197
	ds_read_b32 v197, v197
.LBB0_539:
	s_or_b64 exec, exec, s[4:5]
	v_add_u32_e32 v227, 0xffffff9a, v138
	v_add_u32_e32 v228, 26, v139
	v_cmp_gt_u32_e32 vcc, s97, v228
	v_cmp_gt_i32_e64 s[4:5], s33, v227
	s_and_b64 s[4:5], s[4:5], vcc
	s_and_b64 s[38:39], s[14:15], s[4:5]
	v_mov_b32_e32 v199, 0xff800000
	v_mov_b32_e32 v198, 0xff800000
	s_and_saveexec_b64 s[4:5], s[38:39]
	s_cbranch_execz .LBB0_541
	v_add_u32_e32 v198, 0, v130
	v_add_u32_e32 v198, 0x1c068, v198
	ds_read_b32 v198, v198
.LBB0_541:
	s_or_b64 exec, exec, s[4:5]
	v_add_u32_e32 v229, 0xffffff9b, v138
	v_add_u32_e32 v200, 27, v139
	v_cmp_gt_u32_e32 vcc, s97, v200
	v_cmp_gt_i32_e64 s[4:5], s33, v229
	s_and_b64 s[4:5], s[4:5], vcc
	s_and_b64 s[14:15], s[14:15], s[4:5]
	s_and_saveexec_b64 s[4:5], s[14:15]
	s_cbranch_execz .LBB0_543
	v_add_u32_e32 v199, 0, v130
	v_add_u32_e32 v199, 0x1c06c, v199
	ds_read_b32 v199, v199
.LBB0_543:
	s_or_b64 exec, exec, s[4:5]
	s_waitcnt lgkmcnt(0)
	v_fmac_f32_e32 v184, 0x3e38aa3b, v48
	v_fmac_f32_e32 v185, 0x3e38aa3b, v49
	v_fmac_f32_e32 v186, 0x3e38aa3b, v50
	v_fmac_f32_e32 v187, 0x3e38aa3b, v51
	v_fmac_f32_e32 v188, 0x3e38aa3b, v52
	v_fmac_f32_e32 v189, 0x3e38aa3b, v53
	v_fmac_f32_e32 v190, 0x3e38aa3b, v54
	v_fmac_f32_e32 v191, 0x3e38aa3b, v55
	v_fmac_f32_e32 v192, 0x3e38aa3b, v56
	v_fmac_f32_e32 v193, 0x3e38aa3b, v57
	v_fmac_f32_e32 v194, 0x3e38aa3b, v58
	v_fmac_f32_e32 v195, 0x3e38aa3b, v59
	v_fmac_f32_e32 v196, 0x3e38aa3b, v60
	v_fmac_f32_e32 v197, 0x3e38aa3b, v61
	v_fmac_f32_e32 v198, 0x3e38aa3b, v62
	v_fmac_f32_e32 v199, 0x3e38aa3b, v63
	v_mov_b32_e32 v32, v184
	v_mov_b32_e32 v33, v185
	v_mov_b32_e32 v34, v186
	v_mov_b32_e32 v35, v187
	v_mov_b32_e32 v36, v188
	v_mov_b32_e32 v37, v189
	v_mov_b32_e32 v38, v190
	v_mov_b32_e32 v39, v191
	v_mov_b32_e32 v40, v192
	v_mov_b32_e32 v41, v193
	v_mov_b32_e32 v42, v194
	v_mov_b32_e32 v43, v195
	v_mov_b32_e32 v44, v196
	v_mov_b32_e32 v45, v197
	v_mov_b32_e32 v46, v198
	v_mov_b32_e32 v47, v199

.LBB0_554:
	s_andn2_b64 vcc, exec, s[4:5]
	s_cbranch_vccnz .LBB0_588
	v_add_u32_e32 v137, s35, v133
	v_add_u32_e32 v139, s35, v131
	v_add_u32_e32 v200, 0xffffffa0, v137
	v_add_u32_e32 v201, 32, v139
	s_cmp_gt_i32 s14, -1
	v_cmp_gt_u32_e32 vcc, s97, v201
	v_cmp_gt_i32_e64 s[4:5], s33, v200
	s_cselect_b64 s[14:15], -1, 0
	s_and_b64 s[4:5], s[4:5], vcc
	s_and_b64 s[36:37], s[14:15], s[4:5]
	v_mov_b32_e32 v185, 0xff800000
	v_mov_b32_e32 v184, 0xff800000
	s_and_saveexec_b64 s[4:5], s[36:37]
	s_cbranch_execz .LBB0_557
	v_add_u32_e32 v184, 0x1c080, v136
	ds_read_b32 v184, v184
.LBB0_557:
	s_or_b64 exec, exec, s[4:5]
	v_add_u32_e32 v202, 0xffffffa1, v137
	v_add_u32_e32 v203, 33, v139
	v_cmp_gt_u32_e32 vcc, s97, v203
	v_cmp_gt_i32_e64 s[4:5], s33, v202
	s_and_b64 s[4:5], s[4:5], vcc
	s_and_b64 s[36:37], s[14:15], s[4:5]
	s_and_saveexec_b64 s[4:5], s[36:37]
	s_cbranch_execz .LBB0_559
	v_add_u32_e32 v185, 0x1c084, v136
	ds_read_b32 v185, v185
.LBB0_559:
	s_or_b64 exec, exec, s[4:5]
	v_add_u32_e32 v204, 0xffffffa2, v137
	v_add_u32_e32 v205, 34, v139
	v_cmp_gt_u32_e32 vcc, s97, v205
	v_cmp_gt_i32_e64 s[4:5], s33, v204
	s_and_b64 s[4:5], s[4:5], vcc
	s_and_b64 s[36:37], s[14:15], s[4:5]
	v_mov_b32_e32 v187, 0xff800000
	v_mov_b32_e32 v186, 0xff800000
	s_and_saveexec_b64 s[4:5], s[36:37]
	s_cbranch_execz .LBB0_561
	v_add_u32_e32 v186, 0x1c088, v136
	ds_read_b32 v186, v186
.LBB0_561:
	s_or_b64 exec, exec, s[4:5]
	v_add_u32_e32 v206, 0xffffffa3, v137
	v_add_u32_e32 v207, 35, v139
	v_cmp_gt_u32_e32 vcc, s97, v207
	v_cmp_gt_i32_e64 s[4:5], s33, v206
	s_and_b64 s[4:5], s[4:5], vcc
	s_and_b64 s[36:37], s[14:15], s[4:5]
	s_and_saveexec_b64 s[4:5], s[36:37]
	s_cbranch_execz .LBB0_563
	v_add_u32_e32 v187, 0x1c08c, v136
	ds_read_b32 v187, v187
.LBB0_563:
	s_or_b64 exec, exec, s[4:5]
	v_add_u32_e32 v208, 0xffffffa8, v137
	v_add_u32_e32 v209, 40, v139
	v_cmp_gt_u32_e32 vcc, s97, v209
	v_cmp_gt_i32_e64 s[4:5], s33, v208
	s_and_b64 s[4:5], s[4:5], vcc
	s_and_b64 s[36:37], s[14:15], s[4:5]
	v_mov_b32_e32 v189, 0xff800000
	v_mov_b32_e32 v188, 0xff800000
	s_and_saveexec_b64 s[4:5], s[36:37]
	s_cbranch_execz .LBB0_565
	v_add_u32_e32 v188, 0x1c0a0, v136
	ds_read_b32 v188, v188
.LBB0_565:
	s_or_b64 exec, exec, s[4:5]
	v_add_u32_e32 v210, 0xffffffa9, v137
	v_add_u32_e32 v211, 41, v139
	v_cmp_gt_u32_e32 vcc, s97, v211
	v_cmp_gt_i32_e64 s[4:5], s33, v210
	s_and_b64 s[4:5], s[4:5], vcc
	s_and_b64 s[36:37], s[14:15], s[4:5]
	s_and_saveexec_b64 s[4:5], s[36:37]
	s_cbranch_execz .LBB0_567
	v_add_u32_e32 v189, 0x1c0a4, v136
	ds_read_b32 v189, v189
.LBB0_567:
	s_or_b64 exec, exec, s[4:5]
	v_add_u32_e32 v212, 0xffffffaa, v137
	v_add_u32_e32 v213, 42, v139
	v_cmp_gt_u32_e32 vcc, s97, v213
	v_cmp_gt_i32_e64 s[4:5], s33, v212
	s_and_b64 s[4:5], s[4:5], vcc
	s_and_b64 s[36:37], s[14:15], s[4:5]
	v_mov_b32_e32 v191, 0xff800000
	v_mov_b32_e32 v190, 0xff800000
	s_and_saveexec_b64 s[4:5], s[36:37]
	s_cbranch_execz .LBB0_569
	v_add_u32_e32 v190, 0x1c0a8, v136
	ds_read_b32 v190, v190
.LBB0_569:
	s_or_b64 exec, exec, s[4:5]
	v_add_u32_e32 v214, 0xffffffab, v137
	v_add_u32_e32 v215, 43, v139
	v_cmp_gt_u32_e32 vcc, s97, v215
	v_cmp_gt_i32_e64 s[4:5], s33, v214
	s_and_b64 s[4:5], s[4:5], vcc
	s_and_b64 s[36:37], s[14:15], s[4:5]
	s_and_saveexec_b64 s[4:5], s[36:37]
	s_cbranch_execz .LBB0_571
	v_add_u32_e32 v191, 0x1c0ac, v136
	ds_read_b32 v191, v191
.LBB0_571:
	s_or_b64 exec, exec, s[4:5]
	v_add_u32_e32 v216, 0xffffffb0, v137
	v_add_u32_e32 v217, 48, v139
	v_cmp_gt_u32_e32 vcc, s97, v217
	v_cmp_gt_i32_e64 s[4:5], s33, v216
	s_and_b64 s[4:5], s[4:5], vcc
	s_and_b64 s[36:37], s[14:15], s[4:5]
	v_mov_b32_e32 v193, 0xff800000
	v_mov_b32_e32 v192, 0xff800000
	s_and_saveexec_b64 s[4:5], s[36:37]
	s_cbranch_execz .LBB0_573
	v_add_u32_e32 v192, 0x1c0c0, v136
	ds_read_b32 v192, v192
.LBB0_573:
	s_or_b64 exec, exec, s[4:5]
	v_add_u32_e32 v218, 0xffffffb1, v137
	v_add_u32_e32 v219, 49, v139
	v_cmp_gt_u32_e32 vcc, s97, v219
	v_cmp_gt_i32_e64 s[4:5], s33, v218
	s_and_b64 s[4:5], s[4:5], vcc
	s_and_b64 s[36:37], s[14:15], s[4:5]
	s_and_saveexec_b64 s[4:5], s[36:37]
	s_cbranch_execz .LBB0_575
	v_add_u32_e32 v193, 0x1c0c4, v136
	ds_read_b32 v193, v193
.LBB0_575:
	s_or_b64 exec, exec, s[4:5]
	v_add_u32_e32 v220, 0xffffffb2, v137
	v_add_u32_e32 v221, 50, v139
	v_cmp_gt_u32_e32 vcc, s97, v221
	v_cmp_gt_i32_e64 s[4:5], s33, v220
	s_and_b64 s[4:5], s[4:5], vcc
	s_and_b64 s[36:37], s[14:15], s[4:5]
	v_mov_b32_e32 v195, 0xff800000
	v_mov_b32_e32 v194, 0xff800000
	s_and_saveexec_b64 s[4:5], s[36:37]
	s_cbranch_execz .LBB0_577
	v_add_u32_e32 v194, 0x1c0c8, v136
	ds_read_b32 v194, v194
.LBB0_577:
	s_or_b64 exec, exec, s[4:5]
	v_add_u32_e32 v222, 0xffffffb3, v137
	v_add_u32_e32 v223, 51, v139
	v_cmp_gt_u32_e32 vcc, s97, v223
	v_cmp_gt_i32_e64 s[4:5], s33, v222
	s_and_b64 s[4:5], s[4:5], vcc
	s_and_b64 s[36:37], s[14:15], s[4:5]
	s_and_saveexec_b64 s[4:5], s[36:37]
	s_cbranch_execz .LBB0_579
	v_add_u32_e32 v195, 0x1c0cc, v136
	ds_read_b32 v195, v195
.LBB0_579:
	s_or_b64 exec, exec, s[4:5]
	v_add_u32_e32 v224, 0xffffffb8, v137
	v_add_u32_e32 v225, 56, v139
	v_cmp_gt_u32_e32 vcc, s97, v225
	v_cmp_gt_i32_e64 s[4:5], s33, v224
	s_and_b64 s[4:5], s[4:5], vcc
	s_and_b64 s[36:37], s[14:15], s[4:5]
	v_mov_b32_e32 v197, 0xff800000
	v_mov_b32_e32 v196, 0xff800000
	s_and_saveexec_b64 s[4:5], s[36:37]
	s_cbranch_execz .LBB0_581
	v_add_u32_e32 v196, 0x1c0e0, v136
	ds_read_b32 v196, v196
.LBB0_581:
	s_or_b64 exec, exec, s[4:5]
	v_add_u32_e32 v226, 0xffffffb9, v137
	v_add_u32_e32 v227, 57, v139
	v_cmp_gt_u32_e32 vcc, s97, v227
	v_cmp_gt_i32_e64 s[4:5], s33, v226
	s_and_b64 s[4:5], s[4:5], vcc
	s_and_b64 s[36:37], s[14:15], s[4:5]
	s_and_saveexec_b64 s[4:5], s[36:37]
	s_cbranch_execz .LBB0_583
	v_add_u32_e32 v197, 0x1c0e4, v136
	ds_read_b32 v197, v197
.LBB0_583:
	s_or_b64 exec, exec, s[4:5]
	v_add_u32_e32 v228, 0xffffffba, v137
	v_add_u32_e32 v229, 58, v139
	v_cmp_gt_u32_e32 vcc, s97, v229
	v_cmp_gt_i32_e64 s[4:5], s33, v228
	s_and_b64 s[4:5], s[4:5], vcc
	s_and_b64 s[36:37], s[14:15], s[4:5]
	v_mov_b32_e32 v199, 0xff800000
	v_mov_b32_e32 v198, 0xff800000
	s_and_saveexec_b64 s[4:5], s[36:37]
	s_cbranch_execz .LBB0_585
	v_add_u32_e32 v198, 0x1c0e8, v136
	ds_read_b32 v198, v198
.LBB0_585:
	s_or_b64 exec, exec, s[4:5]
	v_add_u32_e32 v200, 0xffffffbb, v137
	v_add_u32_e32 v201, 59, v139
	v_cmp_gt_u32_e32 vcc, s97, v201
	v_cmp_gt_i32_e64 s[4:5], s33, v200
	s_and_b64 s[4:5], s[4:5], vcc
	s_and_b64 s[14:15], s[14:15], s[4:5]
	s_and_saveexec_b64 s[4:5], s[14:15]
	s_cbranch_execz .LBB0_587
	v_add_u32_e32 v199, 0x1c0ec, v136
	ds_read_b32 v199, v199

.LBB0_609:
	s_lshr_b32 s84, s87, 6
	s_cmp_ge_u32 s84, s89
	s_cselect_b64 s[70:71], -1, 0
	s_cmp_lt_u32 s84, s72
	s_cselect_b64 vcc, -1, 0
	s_and_b64 s[70:71], s[70:71], vcc
	s_andn2_b64 vcc, exec, s[70:71]
	v_add_u32_e32 v155, s76, v152
	s_cbranch_vccnz .LBB0_646
	ds_read_b128 v[32:35], v155
	ds_read_b128 v[156:159], v155 offset:32
	v_sub_u32_e32 v160, s84, v126
	v_cmp_ge_u32_e32 vcc, s84, v133
	v_cmp_lt_u32_e64 s[70:71], s84, v134
	v_max_i32_e32 v160, -7, v160
	s_and_b64 s[70:71], vcc, s[70:71]
	v_add_u32_e32 v160, 7, v160
	s_add_i32 s84, 0, 0x1c000
	s_waitcnt lgkmcnt(0)
	v_mfma_f32_32x32x16_bf16 v[32:47], v[32:35], v[96:99], 0
	v_mfma_f32_32x32x16_bf16 v[32:47], v[156:159], v[100:103], v[32:47]
	ds_read_b128 v[156:159], v155 offset:64
	s_waitcnt lgkmcnt(0)
	v_mfma_f32_32x32x16_bf16 v[32:47], v[156:159], v[104:107], v[32:47]
	ds_read_b128 v[156:159], v155 offset:96
	s_waitcnt lgkmcnt(0)
	v_mfma_f32_32x32x16_bf16 v[32:47], v[156:159], v[108:111], v[32:47]
	v_min_u32_e32 v156, 14, v160
	v_mov_b32_e32 v200, s84
	s_and_b64 s[84:85], s[70:71], s[4:5]
	v_mad_u32_u24 v156, v156, s93, v200
	s_and_b64 vcc, s[84:85], s[6:7]
	v_mov_b32_e32 v185, 0xff800000
	v_mov_b32_e32 v184, 0xff800000
	s_and_saveexec_b64 s[84:85], vcc
	s_cbranch_execz .LBB0_612
	v_lshl_add_u32 v184, v135, 2, v156
	ds_read_b32 v184, v184
.LBB0_612:
	s_or_b64 exec, exec, s[84:85]
	s_and_b64 s[84:85], s[70:71], s[8:9]
	s_and_b64 vcc, s[84:85], s[10:11]
	s_and_saveexec_b64 s[84:85], vcc
	s_cbranch_execz .LBB0_614
	v_lshl_add_u32 v185, v136, 2, v156
	ds_read_b32 v185, v185
.LBB0_614:
	s_or_b64 exec, exec, s[84:85]
	s_and_b64 s[84:85], s[70:71], s[12:13]
	s_and_b64 vcc, s[84:85], s[14:15]
	v_mov_b32_e32 v187, 0xff800000
	v_mov_b32_e32 v186, 0xff800000
	s_and_saveexec_b64 s[84:85], vcc
	s_cbranch_execz .LBB0_616
	v_lshl_add_u32 v186, v137, 2, v156
	ds_read_b32 v186, v186
.LBB0_616:
	s_or_b64 exec, exec, s[84:85]
	s_and_b64 s[84:85], s[70:71], s[16:17]
	s_and_b64 vcc, s[84:85], s[18:19]
	s_and_saveexec_b64 s[84:85], vcc
	s_cbranch_execz .LBB0_618
	v_lshl_add_u32 v187, v138, 2, v156
	ds_read_b32 v187, v187
.LBB0_618:
	s_or_b64 exec, exec, s[84:85]
	s_and_b64 s[84:85], s[70:71], s[20:21]
	s_and_b64 vcc, s[84:85], s[22:23]
	v_mov_b32_e32 v189, 0xff800000
	v_mov_b32_e32 v188, 0xff800000
	s_and_saveexec_b64 s[84:85], vcc
	s_cbranch_execz .LBB0_620
	v_lshl_add_u32 v188, v139, 2, v156
	ds_read_b32 v188, v188
.LBB0_620:
	s_or_b64 exec, exec, s[84:85]
	s_and_b64 s[84:85], s[70:71], s[24:25]
	s_and_b64 vcc, s[84:85], s[26:27]
	s_and_saveexec_b64 s[84:85], vcc
	s_cbranch_execz .LBB0_622
	v_lshl_add_u32 v189, v140, 2, v156
	ds_read_b32 v189, v189
.LBB0_622:
	s_or_b64 exec, exec, s[84:85]
	s_and_b64 s[84:85], s[70:71], s[28:29]
	s_and_b64 vcc, s[84:85], s[30:31]
	v_mov_b32_e32 v191, 0xff800000
	v_mov_b32_e32 v190, 0xff800000
	s_and_saveexec_b64 s[84:85], vcc
	s_cbranch_execz .LBB0_624
	v_lshl_add_u32 v190, v141, 2, v156
	ds_read_b32 v190, v190
.LBB0_624:
	s_or_b64 exec, exec, s[84:85]
	s_and_b64 s[84:85], s[70:71], s[34:35]
	s_and_b64 vcc, s[84:85], s[36:37]
	s_and_saveexec_b64 s[84:85], vcc
	s_cbranch_execz .LBB0_626
	v_lshl_add_u32 v191, v142, 2, v156
	ds_read_b32 v191, v191
.LBB0_626:
	s_or_b64 exec, exec, s[84:85]
	s_and_b64 s[84:85], s[70:71], s[38:39]
	s_and_b64 vcc, s[84:85], s[40:41]
	v_mov_b32_e32 v193, 0xff800000
	v_mov_b32_e32 v192, 0xff800000
	s_and_saveexec_b64 s[84:85], vcc
	s_cbranch_execz .LBB0_628
	v_lshl_add_u32 v192, v143, 2, v156
	ds_read_b32 v192, v192
.LBB0_628:
	s_or_b64 exec, exec, s[84:85]
	s_and_b64 s[84:85], s[70:71], s[42:43]
	s_and_b64 vcc, s[84:85], s[44:45]
	s_and_saveexec_b64 s[84:85], vcc
	s_cbranch_execz .LBB0_630
	v_lshl_add_u32 v193, v144, 2, v156
	ds_read_b32 v193, v193
.LBB0_630:
	s_or_b64 exec, exec, s[84:85]
	s_and_b64 s[84:85], s[70:71], s[46:47]
	s_and_b64 vcc, s[84:85], s[48:49]
	v_mov_b32_e32 v195, 0xff800000
	v_mov_b32_e32 v194, 0xff800000
	s_and_saveexec_b64 s[84:85], vcc
	s_cbranch_execz .LBB0_632
	v_lshl_add_u32 v194, v145, 2, v156
	ds_read_b32 v194, v194
.LBB0_632:
	s_or_b64 exec, exec, s[84:85]
	s_and_b64 s[84:85], s[70:71], s[50:51]
	s_and_b64 vcc, s[84:85], s[52:53]
	s_and_saveexec_b64 s[84:85], vcc
	s_cbranch_execz .LBB0_634
	v_lshl_add_u32 v195, v146, 2, v156
	ds_read_b32 v195, v195
.LBB0_634:
	s_or_b64 exec, exec, s[84:85]
	s_and_b64 s[84:85], s[70:71], s[54:55]
	s_and_b64 vcc, s[84:85], s[56:57]
	v_mov_b32_e32 v197, 0xff800000
	v_mov_b32_e32 v196, 0xff800000
	s_and_saveexec_b64 s[84:85], vcc
	s_cbranch_execz .LBB0_636
	v_lshl_add_u32 v196, v147, 2, v156
	ds_read_b32 v196, v196
.LBB0_636:
	s_or_b64 exec, exec, s[84:85]
	s_and_b64 s[84:85], s[70:71], s[58:59]
	s_and_b64 vcc, s[84:85], s[60:61]
	s_and_saveexec_b64 s[84:85], vcc
	s_cbranch_execz .LBB0_638
	v_lshl_add_u32 v197, v148, 2, v156
	ds_read_b32 v197, v197
.LBB0_638:
	s_or_b64 exec, exec, s[84:85]
	s_and_b64 s[84:85], s[70:71], s[62:63]
	s_and_b64 vcc, s[84:85], s[64:65]
	v_mov_b32_e32 v199, 0xff800000
	v_mov_b32_e32 v198, 0xff800000
	s_and_saveexec_b64 s[84:85], vcc
	s_cbranch_execz .LBB0_640
	v_lshl_add_u32 v198, v149, 2, v156
	ds_read_b32 v198, v198
.LBB0_640:
	s_or_b64 exec, exec, s[84:85]
	s_and_b64 s[70:71], s[70:71], s[66:67]
	s_and_b64 s[84:85], s[70:71], s[68:69]
	s_and_saveexec_b64 s[70:71], s[84:85]
	s_cbranch_execz .LBB0_642
	v_lshl_add_u32 v199, v150, 2, v156
	ds_read_b32 v199, v199
.LBB0_642:
	s_or_b64 exec, exec, s[70:71]
	s_waitcnt lgkmcnt(0)
	v_fmac_f32_e32 v184, 0x3e38aa3b, v32
	v_fmac_f32_e32 v185, 0x3e38aa3b, v33
	v_fmac_f32_e32 v186, 0x3e38aa3b, v34
	v_fmac_f32_e32 v187, 0x3e38aa3b, v35
	v_fmac_f32_e32 v188, 0x3e38aa3b, v36
	v_fmac_f32_e32 v189, 0x3e38aa3b, v37
	v_fmac_f32_e32 v190, 0x3e38aa3b, v38
	v_fmac_f32_e32 v191, 0x3e38aa3b, v39
	v_fmac_f32_e32 v192, 0x3e38aa3b, v40
	v_fmac_f32_e32 v193, 0x3e38aa3b, v41
	v_fmac_f32_e32 v194, 0x3e38aa3b, v42
	v_fmac_f32_e32 v195, 0x3e38aa3b, v43
	v_fmac_f32_e32 v196, 0x3e38aa3b, v44
	v_fmac_f32_e32 v197, 0x3e38aa3b, v45
	v_fmac_f32_e32 v198, 0x3e38aa3b, v46
	v_fmac_f32_e32 v199, 0x3e38aa3b, v47
	v_mov_b32_e32 v158, v184
	v_mov_b32_e32 v157, v185
	v_mov_b32_e32 v33, v186
	v_mov_b32_e32 v32, v187
	v_mov_b32_e32 v35, v188
	v_mov_b32_e32 v34, v189
	v_mov_b32_e32 v37, v190
	v_mov_b32_e32 v36, v191
	v_mov_b32_e32 v39, v192
	v_mov_b32_e32 v38, v193
	v_mov_b32_e32 v41, v194
	v_mov_b32_e32 v40, v195
	v_mov_b32_e32 v43, v196
	v_mov_b32_e32 v42, v197
	v_mov_b32_e32 v45, v198
	v_mov_b32_e32 v44, v199
	v_max_f32_e32 v46, v157, v157
	v_max_f32_e32 v47, v158, v158
	v_max_f32_e32 v46, v47, v46
	v_max3_f32 v46, v46, v33, v32
	v_max3_f32 v46, v46, v35, v34
	v_max3_f32 v46, v46, v37, v36
	v_max3_f32 v46, v46, v39, v38
	v_max3_f32 v46, v46, v41, v40
	v_max3_f32 v46, v46, v43, v42
	v_max3_f32 v46, v46, v45, v44
	v_mov_b32_e32 v47, v46
	s_nop 1
	v_permlane32_swap_b32_e32 v46, v47
	v_max3_f32 v156, v154, v46, v47
	v_cmp_neq_f32_e32 vcc, v156, v154
	s_cbranch_vccz .LBB0_647
	v_sub_f32_e32 v46, v154, v156
	v_exp_f32_e32 v46, v46
	s_and_saveexec_b64 s[70:71], s[2:3]
	ds_write_b32 v130, v46
	s_or_b64 exec, exec, s[70:71]
	v_mul_f32_e32 v153, v153, v46
	v_add_u32_e32 v46, s88, v232
	ds_read_b128 v[160:163], v46
	ds_read_b128 v[164:167], v46 offset:32
	ds_read_b128 v[168:171], v46 offset:64
	ds_read_b128 v[172:175], v46 offset:96
	s_waitcnt lgkmcnt(0)
	v_pk_mul_f32 v[2:3], v[2:3], v[162:163]
	v_pk_mul_f32 v[4:5], v[4:5], v[164:165]
	v_pk_mul_f32 v[8:9], v[8:9], v[168:169]
	v_pk_mul_f32 v[12:13], v[12:13], v[172:173]
	v_pk_mul_f32 v[14:15], v[14:15], v[174:175]
	v_pk_mul_f32 v[10:11], v[10:11], v[170:171]
	v_pk_mul_f32 v[6:7], v[6:7], v[166:167]
	v_pk_mul_f32 v[0:1], v[0:1], v[160:161]
	v_pk_mul_f32 v[28:29], v[28:29], v[172:173]
	v_pk_mul_f32 v[24:25], v[24:25], v[168:169]
	v_pk_mul_f32 v[20:21], v[20:21], v[164:165]
	v_pk_mul_f32 v[30:31], v[30:31], v[174:175]
	v_pk_mul_f32 v[26:27], v[26:27], v[170:171]
	v_pk_mul_f32 v[22:23], v[22:23], v[166:167]
	v_pk_mul_f32 v[18:19], v[18:19], v[162:163]
	v_pk_mul_f32 v[16:17], v[16:17], v[160:161]
	s_branch .LBB0_648

.LBB0_649:
	s_add_i32 s70, s87, 64
	s_lshr_b32 s84, s70, 6
	s_cmp_ge_u32 s84, s89
	s_cselect_b64 s[70:71], -1, 0
	s_cmp_lt_u32 s84, s72
	s_cselect_b64 vcc, -1, 0
	s_and_b64 s[70:71], s[70:71], vcc
	s_andn2_b64 vcc, exec, s[70:71]
	s_cbranch_vccnz .LBB0_608
	ds_read_b128 v[32:35], v155 offset:9216
	ds_read_b128 v[158:161], v155 offset:9248
	v_sub_u32_e32 v154, s84, v126
	v_cmp_ge_u32_e32 vcc, s84, v133
	v_cmp_lt_u32_e64 s[70:71], s84, v134
	v_max_i32_e32 v154, -7, v154
	s_and_b64 s[70:71], vcc, s[70:71]
	v_add_u32_e32 v154, 7, v154
	s_add_i32 s84, 0, 0x1c000
	s_waitcnt lgkmcnt(0)
	v_mfma_f32_32x32x16_bf16 v[32:47], v[32:35], v[96:99], 0
	v_min_u32_e32 v154, 14, v154
	v_mov_b32_e32 v184, 0xff800000
	v_mfma_f32_32x32x16_bf16 v[32:47], v[158:161], v[100:103], v[32:47]
	ds_read_b128 v[158:161], v155 offset:9280
	s_waitcnt lgkmcnt(0)
	v_mfma_f32_32x32x16_bf16 v[32:47], v[158:161], v[104:107], v[32:47]
	ds_read_b128 v[158:161], v155 offset:9312
	v_mov_b32_e32 v155, s84
	s_and_b64 s[84:85], s[70:71], s[4:5]
	v_mad_u32_u24 v154, v154, s93, v155
	s_and_b64 vcc, s[84:85], s[6:7]
	v_mov_b32_e32 v185, 0xff800000
	s_waitcnt lgkmcnt(0)
	v_mfma_f32_32x32x16_bf16 v[32:47], v[158:161], v[108:111], v[32:47]
	s_and_saveexec_b64 s[84:85], vcc
	s_cbranch_execz .LBB0_652
	v_lshl_add_u32 v184, v135, 2, v154
	ds_read_b32 v184, v184
.LBB0_652:
	s_or_b64 exec, exec, s[84:85]
	s_and_b64 s[84:85], s[70:71], s[8:9]
	s_and_b64 vcc, s[84:85], s[10:11]
	s_and_saveexec_b64 s[84:85], vcc
	s_cbranch_execz .LBB0_654
	v_lshl_add_u32 v185, v136, 2, v154
	ds_read_b32 v185, v185
.LBB0_654:
	s_or_b64 exec, exec, s[84:85]
	s_and_b64 s[84:85], s[70:71], s[12:13]
	s_and_b64 vcc, s[84:85], s[14:15]
	s_nop 1
	v_mov_b32_e32 v187, 0xff800000
	v_mov_b32_e32 v186, 0xff800000
	s_and_saveexec_b64 s[84:85], vcc
	s_cbranch_execz .LBB0_656
	v_lshl_add_u32 v186, v137, 2, v154
	ds_read_b32 v186, v186
.LBB0_656:
	s_or_b64 exec, exec, s[84:85]
	s_and_b64 s[84:85], s[70:71], s[16:17]
	s_and_b64 vcc, s[84:85], s[18:19]
	s_and_saveexec_b64 s[84:85], vcc
	s_cbranch_execz .LBB0_658
	v_lshl_add_u32 v187, v138, 2, v154
	ds_read_b32 v187, v187
.LBB0_658:
	s_or_b64 exec, exec, s[84:85]
	s_and_b64 s[84:85], s[70:71], s[20:21]
	s_and_b64 vcc, s[84:85], s[22:23]
	v_mov_b32_e32 v189, 0xff800000
	v_mov_b32_e32 v188, 0xff800000
	s_and_saveexec_b64 s[84:85], vcc
	s_cbranch_execz .LBB0_660
	v_lshl_add_u32 v188, v139, 2, v154
	ds_read_b32 v188, v188
.LBB0_660:
	s_or_b64 exec, exec, s[84:85]
	s_and_b64 s[84:85], s[70:71], s[24:25]
	s_and_b64 vcc, s[84:85], s[26:27]
	s_and_saveexec_b64 s[84:85], vcc
	s_cbranch_execz .LBB0_662
	v_lshl_add_u32 v189, v140, 2, v154
	ds_read_b32 v189, v189
.LBB0_662:
	s_or_b64 exec, exec, s[84:85]
	s_and_b64 s[84:85], s[70:71], s[28:29]
	s_and_b64 vcc, s[84:85], s[30:31]
	v_mov_b32_e32 v191, 0xff800000
	v_mov_b32_e32 v190, 0xff800000
	s_and_saveexec_b64 s[84:85], vcc
	s_cbranch_execz .LBB0_664
	v_lshl_add_u32 v190, v141, 2, v154
	ds_read_b32 v190, v190
.LBB0_664:
	s_or_b64 exec, exec, s[84:85]
	s_and_b64 s[84:85], s[70:71], s[34:35]
	s_and_b64 vcc, s[84:85], s[36:37]
	s_and_saveexec_b64 s[84:85], vcc
	s_cbranch_execz .LBB0_666
	v_lshl_add_u32 v191, v142, 2, v154
	ds_read_b32 v191, v191
.LBB0_666:
	s_or_b64 exec, exec, s[84:85]
	s_and_b64 s[84:85], s[70:71], s[38:39]
	s_and_b64 vcc, s[84:85], s[40:41]
	v_mov_b32_e32 v193, 0xff800000
	v_mov_b32_e32 v192, 0xff800000
	s_and_saveexec_b64 s[84:85], vcc
	s_cbranch_execz .LBB0_668
	v_lshl_add_u32 v192, v143, 2, v154
	ds_read_b32 v192, v192
.LBB0_668:
	s_or_b64 exec, exec, s[84:85]
	s_and_b64 s[84:85], s[70:71], s[42:43]
	s_and_b64 vcc, s[84:85], s[44:45]
	s_and_saveexec_b64 s[84:85], vcc
	s_cbranch_execz .LBB0_670
	v_lshl_add_u32 v193, v144, 2, v154
	ds_read_b32 v193, v193
.LBB0_670:
	s_or_b64 exec, exec, s[84:85]
	s_and_b64 s[84:85], s[70:71], s[46:47]
	s_and_b64 vcc, s[84:85], s[48:49]
	v_mov_b32_e32 v195, 0xff800000
	v_mov_b32_e32 v194, 0xff800000
	s_and_saveexec_b64 s[84:85], vcc
	s_cbranch_execz .LBB0_672
	v_lshl_add_u32 v194, v145, 2, v154
	ds_read_b32 v194, v194
.LBB0_672:
	s_or_b64 exec, exec, s[84:85]
	s_and_b64 s[84:85], s[70:71], s[50:51]
	s_and_b64 vcc, s[84:85], s[52:53]
	s_and_saveexec_b64 s[84:85], vcc
	s_cbranch_execz .LBB0_674
	v_lshl_add_u32 v195, v146, 2, v154
	ds_read_b32 v195, v195
.LBB0_674:
	s_or_b64 exec, exec, s[84:85]
	s_and_b64 s[84:85], s[70:71], s[54:55]
	s_and_b64 vcc, s[84:85], s[56:57]
	v_mov_b32_e32 v197, 0xff800000
	v_mov_b32_e32 v196, 0xff800000
	s_and_saveexec_b64 s[84:85], vcc
	s_cbranch_execz .LBB0_676
	v_lshl_add_u32 v196, v147, 2, v154
	ds_read_b32 v196, v196
.LBB0_676:
	s_or_b64 exec, exec, s[84:85]
	s_and_b64 s[84:85], s[70:71], s[58:59]
	s_and_b64 vcc, s[84:85], s[60:61]
	s_and_saveexec_b64 s[84:85], vcc
	s_cbranch_execz .LBB0_678
	v_lshl_add_u32 v197, v148, 2, v154
	ds_read_b32 v197, v197
.LBB0_678:
	s_or_b64 exec, exec, s[84:85]
	s_and_b64 s[84:85], s[70:71], s[62:63]
	s_and_b64 vcc, s[84:85], s[64:65]
	v_mov_b32_e32 v199, 0xff800000
	v_mov_b32_e32 v198, 0xff800000
	s_and_saveexec_b64 s[84:85], vcc
	s_cbranch_execz .LBB0_680
	v_lshl_add_u32 v198, v149, 2, v154
	ds_read_b32 v198, v198
.LBB0_680:
	s_or_b64 exec, exec, s[84:85]
	s_and_b64 s[70:71], s[70:71], s[66:67]
	s_and_b64 s[84:85], s[70:71], s[68:69]
	s_and_saveexec_b64 s[70:71], s[84:85]
	s_cbranch_execz .LBB0_682
	v_lshl_add_u32 v199, v150, 2, v154
	ds_read_b32 v199, v199
.LBB0_682:
	s_or_b64 exec, exec, s[70:71]
	s_waitcnt lgkmcnt(0)
	v_fmac_f32_e32 v184, 0x3e38aa3b, v32
	v_fmac_f32_e32 v185, 0x3e38aa3b, v33
	v_fmac_f32_e32 v186, 0x3e38aa3b, v34
	v_fmac_f32_e32 v187, 0x3e38aa3b, v35
	v_fmac_f32_e32 v188, 0x3e38aa3b, v36
	v_fmac_f32_e32 v189, 0x3e38aa3b, v37
	v_fmac_f32_e32 v190, 0x3e38aa3b, v38
	v_fmac_f32_e32 v191, 0x3e38aa3b, v39
	v_fmac_f32_e32 v192, 0x3e38aa3b, v40
	v_fmac_f32_e32 v193, 0x3e38aa3b, v41
	v_fmac_f32_e32 v194, 0x3e38aa3b, v42
	v_fmac_f32_e32 v195, 0x3e38aa3b, v43
	v_fmac_f32_e32 v196, 0x3e38aa3b, v44
	v_fmac_f32_e32 v197, 0x3e38aa3b, v45
	v_fmac_f32_e32 v198, 0x3e38aa3b, v46
	v_fmac_f32_e32 v199, 0x3e38aa3b, v47
	v_mov_b32_e32 v157, v184
	v_mov_b32_e32 v155, v185
	v_mov_b32_e32 v33, v186
	v_mov_b32_e32 v32, v187
	v_mov_b32_e32 v35, v188
	v_mov_b32_e32 v34, v189
	v_mov_b32_e32 v37, v190
	v_mov_b32_e32 v36, v191
	v_mov_b32_e32 v39, v192
	v_mov_b32_e32 v38, v193
	v_mov_b32_e32 v41, v194
	v_mov_b32_e32 v40, v195
	v_mov_b32_e32 v43, v196
	v_mov_b32_e32 v42, v197
	v_mov_b32_e32 v45, v198
	v_mov_b32_e32 v44, v199
	v_max_f32_e32 v46, v155, v155
	v_max_f32_e32 v47, v157, v157
	v_max_f32_e32 v46, v47, v46
	v_max3_f32 v46, v46, v33, v32
	v_max3_f32 v46, v46, v35, v34
	v_max3_f32 v46, v46, v37, v36
	v_max3_f32 v46, v46, v39, v38
	v_max3_f32 v46, v46, v41, v40
	v_max3_f32 v46, v46, v43, v42
	v_max3_f32 v46, v46, v45, v44
	v_mov_b32_e32 v47, v46
	s_nop 1
	v_permlane32_swap_b32_e32 v46, v47
	v_max3_f32 v154, v156, v46, v47
	v_cmp_neq_f32_e32 vcc, v154, v156
	s_cbranch_vccz .LBB0_686
	v_sub_f32_e32 v46, v156, v154
	v_exp_f32_e32 v46, v46
	s_and_saveexec_b64 s[70:71], s[2:3]
	ds_write_b32 v130, v46
	s_or_b64 exec, exec, s[70:71]
	v_mul_f32_e32 v153, v153, v46
	v_add_u32_e32 v46, s88, v232
	ds_read_b128 v[158:161], v46
	ds_read_b128 v[162:165], v46 offset:32
	ds_read_b128 v[166:169], v46 offset:64
	ds_read_b128 v[170:173], v46 offset:96
	s_waitcnt lgkmcnt(0)
	v_pk_mul_f32 v[2:3], v[2:3], v[160:161]
	v_pk_mul_f32 v[4:5], v[4:5], v[162:163]
	v_pk_mul_f32 v[8:9], v[8:9], v[166:167]
	v_pk_mul_f32 v[12:13], v[12:13], v[170:171]
	v_pk_mul_f32 v[14:15], v[14:15], v[172:173]
	v_pk_mul_f32 v[10:11], v[10:11], v[168:169]
	v_pk_mul_f32 v[6:7], v[6:7], v[164:165]
	v_pk_mul_f32 v[0:1], v[0:1], v[158:159]
	v_pk_mul_f32 v[28:29], v[28:29], v[170:171]
	v_pk_mul_f32 v[24:25], v[24:25], v[166:167]
	v_pk_mul_f32 v[20:21], v[20:21], v[162:163]
	v_pk_mul_f32 v[30:31], v[30:31], v[172:173]
	v_pk_mul_f32 v[26:27], v[26:27], v[168:169]
	v_pk_mul_f32 v[22:23], v[22:23], v[164:165]
	v_pk_mul_f32 v[18:19], v[18:19], v[160:161]
	v_pk_mul_f32 v[16:17], v[16:17], v[158:159]
	s_branch .LBB0_687

.LBB0_705:
	s_andn2_b64 vcc, exec, s[10:11]
	s_cbranch_vccnz .LBB0_739
	v_add_u32_e32 v94, s24, v89
	s_cmp_gt_i32 s12, -1
	v_add_u32_e32 v95, s24, v87
	v_subrev_u32_e32 v200, 64, v94
	s_cselect_b64 s[10:11], -1, 0
	v_cmp_gt_u32_e32 vcc, s37, v95
	s_and_b64 s[12:13], s[10:11], vcc
	v_cmp_gt_i32_e32 vcc, s20, v200
	s_and_b64 s[30:31], s[12:13], vcc
	v_mov_b32_e32 v185, 0xff800000
	v_mov_b32_e32 v184, 0xff800000
	s_and_saveexec_b64 s[12:13], s[30:31]
	s_cbranch_execz .LBB0_708
	v_add_u32_e32 v184, 0, v88
	ds_read_b32 v184, v184
.LBB0_708:
	s_or_b64 exec, exec, s[12:13]
	v_add_u32_e32 v201, 1, v95
	v_subrev_u32_e32 v202, 63, v94
	v_cmp_gt_u32_e32 vcc, s37, v201
	s_and_b64 s[12:13], s[10:11], vcc
	v_cmp_gt_i32_e32 vcc, s20, v202
	s_and_b64 s[30:31], s[12:13], vcc
	s_and_saveexec_b64 s[12:13], s[30:31]
	s_cbranch_execz .LBB0_710
	v_add_u32_e32 v185, 0, v86
	v_add_u32_e32 v185, 0x1c004, v185
	ds_read_b32 v185, v185
.LBB0_710:
	s_or_b64 exec, exec, s[12:13]
	v_add_u32_e32 v203, 2, v95
	v_subrev_u32_e32 v204, 62, v94
	v_cmp_gt_u32_e32 vcc, s37, v203
	s_and_b64 s[12:13], s[10:11], vcc
	v_cmp_gt_i32_e32 vcc, s20, v204
	s_and_b64 s[30:31], s[12:13], vcc
	v_mov_b32_e32 v187, 0xff800000
	v_mov_b32_e32 v186, 0xff800000
	s_and_saveexec_b64 s[12:13], s[30:31]
	s_cbranch_execz .LBB0_712
	v_add_u32_e32 v186, 0, v86
	v_add_u32_e32 v186, 0x1c008, v186
	ds_read_b32 v186, v186
.LBB0_712:
	s_or_b64 exec, exec, s[12:13]
	v_add_u32_e32 v205, 3, v95
	v_subrev_u32_e32 v206, 61, v94
	v_cmp_gt_u32_e32 vcc, s37, v205
	s_and_b64 s[12:13], s[10:11], vcc
	v_cmp_gt_i32_e32 vcc, s20, v206
	s_and_b64 s[30:31], s[12:13], vcc
	s_and_saveexec_b64 s[12:13], s[30:31]
	s_cbranch_execz .LBB0_714
	v_add_u32_e32 v187, 0, v86
	v_add_u32_e32 v187, 0x1c00c, v187
	ds_read_b32 v187, v187
.LBB0_714:
	s_or_b64 exec, exec, s[12:13]
	v_add_u32_e32 v207, 8, v95
	v_subrev_u32_e32 v208, 56, v94
	v_cmp_gt_u32_e32 vcc, s37, v207
	s_and_b64 s[12:13], s[10:11], vcc
	v_cmp_gt_i32_e32 vcc, s20, v208
	s_and_b64 s[30:31], s[12:13], vcc
	v_mov_b32_e32 v189, 0xff800000
	v_mov_b32_e32 v188, 0xff800000
	s_and_saveexec_b64 s[12:13], s[30:31]
	s_cbranch_execz .LBB0_716
	v_add_u32_e32 v188, 0, v86
	v_add_u32_e32 v188, 0x1c020, v188
	ds_read_b32 v188, v188
.LBB0_716:
	s_or_b64 exec, exec, s[12:13]
	v_add_u32_e32 v209, 9, v95
	v_subrev_u32_e32 v210, 55, v94
	v_cmp_gt_u32_e32 vcc, s37, v209
	s_and_b64 s[12:13], s[10:11], vcc
	v_cmp_gt_i32_e32 vcc, s20, v210
	s_and_b64 s[30:31], s[12:13], vcc
	s_and_saveexec_b64 s[12:13], s[30:31]
	s_cbranch_execz .LBB0_718
	v_add_u32_e32 v189, 0, v86
	v_add_u32_e32 v189, 0x1c024, v189
	ds_read_b32 v189, v189
.LBB0_718:
	s_or_b64 exec, exec, s[12:13]
	v_add_u32_e32 v211, 10, v95
	v_subrev_u32_e32 v212, 54, v94
	v_cmp_gt_u32_e32 vcc, s37, v211
	s_and_b64 s[12:13], s[10:11], vcc
	v_cmp_gt_i32_e32 vcc, s20, v212
	s_and_b64 s[30:31], s[12:13], vcc
	v_mov_b32_e32 v191, 0xff800000
	v_mov_b32_e32 v190, 0xff800000
	s_and_saveexec_b64 s[12:13], s[30:31]
	s_cbranch_execz .LBB0_720
	v_add_u32_e32 v190, 0, v86
	v_add_u32_e32 v190, 0x1c028, v190
	ds_read_b32 v190, v190
.LBB0_720:
	s_or_b64 exec, exec, s[12:13]
	v_add_u32_e32 v213, 11, v95
	v_subrev_u32_e32 v214, 53, v94
	v_cmp_gt_u32_e32 vcc, s37, v213
	s_and_b64 s[12:13], s[10:11], vcc
	v_cmp_gt_i32_e32 vcc, s20, v214
	s_and_b64 s[30:31], s[12:13], vcc
	s_and_saveexec_b64 s[12:13], s[30:31]
	s_cbranch_execz .LBB0_722
	v_add_u32_e32 v191, 0, v86
	v_add_u32_e32 v191, 0x1c02c, v191
	ds_read_b32 v191, v191
.LBB0_722:
	s_or_b64 exec, exec, s[12:13]
	v_add_u32_e32 v215, 16, v95
	v_subrev_u32_e32 v216, 48, v94
	v_cmp_gt_u32_e32 vcc, s37, v215
	s_and_b64 s[12:13], s[10:11], vcc
	v_cmp_gt_i32_e32 vcc, s20, v216
	s_and_b64 s[30:31], s[12:13], vcc
	v_mov_b32_e32 v193, 0xff800000
	v_mov_b32_e32 v192, 0xff800000
	s_and_saveexec_b64 s[12:13], s[30:31]
	s_cbranch_execz .LBB0_724
	v_add_u32_e32 v192, 0, v86
	v_add_u32_e32 v192, 0x1c040, v192
	ds_read_b32 v192, v192
.LBB0_724:
	s_or_b64 exec, exec, s[12:13]
	v_add_u32_e32 v217, 17, v95
	v_subrev_u32_e32 v218, 47, v94
	v_cmp_gt_u32_e32 vcc, s37, v217
	s_and_b64 s[12:13], s[10:11], vcc
	v_cmp_gt_i32_e32 vcc, s20, v218
	s_and_b64 s[30:31], s[12:13], vcc
	s_and_saveexec_b64 s[12:13], s[30:31]
	s_cbranch_execz .LBB0_726
	v_add_u32_e32 v193, 0, v86
	v_add_u32_e32 v193, 0x1c044, v193
	ds_read_b32 v193, v193
.LBB0_726:
	s_or_b64 exec, exec, s[12:13]
	v_add_u32_e32 v219, 18, v95
	v_subrev_u32_e32 v220, 46, v94
	v_cmp_gt_u32_e32 vcc, s37, v219
	s_and_b64 s[12:13], s[10:11], vcc
	v_cmp_gt_i32_e32 vcc, s20, v220
	s_and_b64 s[30:31], s[12:13], vcc
	v_mov_b32_e32 v195, 0xff800000
	v_mov_b32_e32 v194, 0xff800000
	s_and_saveexec_b64 s[12:13], s[30:31]
	s_cbranch_execz .LBB0_728
	v_add_u32_e32 v194, 0, v86
	v_add_u32_e32 v194, 0x1c048, v194
	ds_read_b32 v194, v194
.LBB0_728:
	s_or_b64 exec, exec, s[12:13]
	v_add_u32_e32 v221, 19, v95
	v_subrev_u32_e32 v222, 45, v94
	v_cmp_gt_u32_e32 vcc, s37, v221
	s_and_b64 s[12:13], s[10:11], vcc
	v_cmp_gt_i32_e32 vcc, s20, v222
	s_and_b64 s[30:31], s[12:13], vcc
	s_and_saveexec_b64 s[12:13], s[30:31]
	s_cbranch_execz .LBB0_730
	v_add_u32_e32 v195, 0, v86
	v_add_u32_e32 v195, 0x1c04c, v195
	ds_read_b32 v195, v195
.LBB0_730:
	s_or_b64 exec, exec, s[12:13]
	v_add_u32_e32 v223, 24, v95
	v_subrev_u32_e32 v224, 40, v94
	v_cmp_gt_u32_e32 vcc, s37, v223
	s_and_b64 s[12:13], s[10:11], vcc
	v_cmp_gt_i32_e32 vcc, s20, v224
	s_and_b64 s[30:31], s[12:13], vcc
	v_mov_b32_e32 v197, 0xff800000
	v_mov_b32_e32 v196, 0xff800000
	s_and_saveexec_b64 s[12:13], s[30:31]
	s_cbranch_execz .LBB0_732
	v_add_u32_e32 v196, 0, v86
	v_add_u32_e32 v196, 0x1c060, v196
	ds_read_b32 v196, v196
.LBB0_732:
	s_or_b64 exec, exec, s[12:13]
	v_add_u32_e32 v225, 25, v95
	v_subrev_u32_e32 v226, 39, v94
	v_cmp_gt_u32_e32 vcc, s37, v225
	s_and_b64 s[12:13], s[10:11], vcc
	v_cmp_gt_i32_e32 vcc, s20, v226
	s_and_b64 s[30:31], s[12:13], vcc
	s_and_saveexec_b64 s[12:13], s[30:31]
	s_cbranch_execz .LBB0_734
	v_add_u32_e32 v197, 0, v86
	v_add_u32_e32 v197, 0x1c064, v197
	ds_read_b32 v197, v197
.LBB0_734:
	s_or_b64 exec, exec, s[12:13]
	v_add_u32_e32 v227, 26, v95
	v_subrev_u32_e32 v228, 38, v94
	v_cmp_gt_u32_e32 vcc, s37, v227
	s_and_b64 s[12:13], s[10:11], vcc
	v_cmp_gt_i32_e32 vcc, s20, v228
	s_and_b64 s[30:31], s[12:13], vcc
	v_mov_b32_e32 v199, 0xff800000
	v_mov_b32_e32 v198, 0xff800000
	s_and_saveexec_b64 s[12:13], s[30:31]
	s_cbranch_execz .LBB0_736
	v_add_u32_e32 v198, 0, v86
	v_add_u32_e32 v198, 0x1c068, v198
	ds_read_b32 v198, v198
.LBB0_736:
	s_or_b64 exec, exec, s[12:13]
	v_add_u32_e32 v229, 27, v95
	v_subrev_u32_e32 v200, 37, v94
	v_cmp_gt_u32_e32 vcc, s37, v229
	s_and_b64 s[10:11], s[10:11], vcc
	v_cmp_gt_i32_e32 vcc, s20, v200
	s_and_b64 s[12:13], s[10:11], vcc
	s_and_saveexec_b64 s[10:11], s[12:13]
	s_cbranch_execz .LBB0_738
	v_add_u32_e32 v199, 0, v86
	v_add_u32_e32 v199, 0x1c06c, v199
	ds_read_b32 v199, v199
.LBB0_738:
	s_or_b64 exec, exec, s[10:11]
	s_waitcnt lgkmcnt(0)
	v_fmac_f32_e32 v184, 0x3e38aa3b, v48
	v_fmac_f32_e32 v185, 0x3e38aa3b, v49
	v_fmac_f32_e32 v186, 0x3e38aa3b, v50
	v_fmac_f32_e32 v187, 0x3e38aa3b, v51
	v_fmac_f32_e32 v188, 0x3e38aa3b, v52
	v_fmac_f32_e32 v189, 0x3e38aa3b, v53
	v_fmac_f32_e32 v190, 0x3e38aa3b, v54
	v_fmac_f32_e32 v191, 0x3e38aa3b, v55
	v_fmac_f32_e32 v192, 0x3e38aa3b, v56
	v_fmac_f32_e32 v193, 0x3e38aa3b, v57
	v_fmac_f32_e32 v194, 0x3e38aa3b, v58
	v_fmac_f32_e32 v195, 0x3e38aa3b, v59
	v_fmac_f32_e32 v196, 0x3e38aa3b, v60
	v_fmac_f32_e32 v197, 0x3e38aa3b, v61
	v_fmac_f32_e32 v198, 0x3e38aa3b, v62
	v_fmac_f32_e32 v199, 0x3e38aa3b, v63
	v_mov_b32_e32 v32, v184
	v_mov_b32_e32 v33, v185
	v_mov_b32_e32 v34, v186
	v_mov_b32_e32 v35, v187
	v_mov_b32_e32 v36, v188
	v_mov_b32_e32 v37, v189
	v_mov_b32_e32 v38, v190
	v_mov_b32_e32 v39, v191
	v_mov_b32_e32 v40, v192
	v_mov_b32_e32 v41, v193
	v_mov_b32_e32 v42, v194
	v_mov_b32_e32 v43, v195
	v_mov_b32_e32 v44, v196
	v_mov_b32_e32 v45, v197
	v_mov_b32_e32 v46, v198
	v_mov_b32_e32 v47, v199

.LBB0_749:
	s_andn2_b64 vcc, exec, s[10:11]
	s_cbranch_vccnz .LBB0_783
	v_add_u32_e32 v95, s24, v87
	v_add_u32_e32 v93, s24, v89
	s_cmp_gt_i32 s12, -1
	v_add_u32_e32 v200, 32, v95
	v_subrev_u32_e32 v201, 32, v93
	s_cselect_b64 s[10:11], -1, 0
	v_cmp_gt_u32_e32 vcc, s37, v200
	s_and_b64 s[12:13], s[10:11], vcc
	v_cmp_gt_i32_e32 vcc, s20, v201
	s_and_b64 s[28:29], s[12:13], vcc
	v_mov_b32_e32 v185, 0xff800000
	v_mov_b32_e32 v184, 0xff800000
	s_and_saveexec_b64 s[12:13], s[28:29]
	s_cbranch_execz .LBB0_752
	v_add_u32_e32 v184, 0x1c080, v92
	ds_read_b32 v184, v184
.LBB0_752:
	s_or_b64 exec, exec, s[12:13]
	v_add_u32_e32 v202, 33, v95
	v_subrev_u32_e32 v203, 31, v93
	v_cmp_gt_u32_e32 vcc, s37, v202
	s_and_b64 s[12:13], s[10:11], vcc
	v_cmp_gt_i32_e32 vcc, s20, v203
	s_and_b64 s[28:29], s[12:13], vcc
	s_and_saveexec_b64 s[12:13], s[28:29]
	s_cbranch_execz .LBB0_754
	v_add_u32_e32 v185, 0x1c084, v92
	ds_read_b32 v185, v185
.LBB0_754:
	s_or_b64 exec, exec, s[12:13]
	v_add_u32_e32 v204, 34, v95
	v_subrev_u32_e32 v205, 30, v93
	v_cmp_gt_u32_e32 vcc, s37, v204
	s_and_b64 s[12:13], s[10:11], vcc
	v_cmp_gt_i32_e32 vcc, s20, v205
	s_and_b64 s[28:29], s[12:13], vcc
	v_mov_b32_e32 v187, 0xff800000
	v_mov_b32_e32 v186, 0xff800000
	s_and_saveexec_b64 s[12:13], s[28:29]
	s_cbranch_execz .LBB0_756
	v_add_u32_e32 v186, 0x1c088, v92
	ds_read_b32 v186, v186
.LBB0_756:
	s_or_b64 exec, exec, s[12:13]
	v_add_u32_e32 v206, 35, v95
	v_subrev_u32_e32 v207, 29, v93
	v_cmp_gt_u32_e32 vcc, s37, v206
	s_and_b64 s[12:13], s[10:11], vcc
	v_cmp_gt_i32_e32 vcc, s20, v207
	s_and_b64 s[28:29], s[12:13], vcc
	s_and_saveexec_b64 s[12:13], s[28:29]
	s_cbranch_execz .LBB0_758
	v_add_u32_e32 v187, 0x1c08c, v92
	ds_read_b32 v187, v187
.LBB0_758:
	s_or_b64 exec, exec, s[12:13]
	v_add_u32_e32 v208, 40, v95
	v_subrev_u32_e32 v209, 24, v93
	v_cmp_gt_u32_e32 vcc, s37, v208
	s_and_b64 s[12:13], s[10:11], vcc
	v_cmp_gt_i32_e32 vcc, s20, v209
	s_and_b64 s[28:29], s[12:13], vcc
	v_mov_b32_e32 v189, 0xff800000
	v_mov_b32_e32 v188, 0xff800000
	s_and_saveexec_b64 s[12:13], s[28:29]
	s_cbranch_execz .LBB0_760
	v_add_u32_e32 v188, 0x1c0a0, v92
	ds_read_b32 v188, v188
.LBB0_760:
	s_or_b64 exec, exec, s[12:13]
	v_add_u32_e32 v210, 41, v95
	v_subrev_u32_e32 v211, 23, v93
	v_cmp_gt_u32_e32 vcc, s37, v210
	s_and_b64 s[12:13], s[10:11], vcc
	v_cmp_gt_i32_e32 vcc, s20, v211
	s_and_b64 s[28:29], s[12:13], vcc
	s_and_saveexec_b64 s[12:13], s[28:29]
	s_cbranch_execz .LBB0_762
	v_add_u32_e32 v189, 0x1c0a4, v92
	ds_read_b32 v189, v189
.LBB0_762:
	s_or_b64 exec, exec, s[12:13]
	v_add_u32_e32 v212, 42, v95
	v_subrev_u32_e32 v213, 22, v93
	v_cmp_gt_u32_e32 vcc, s37, v212
	s_and_b64 s[12:13], s[10:11], vcc
	v_cmp_gt_i32_e32 vcc, s20, v213
	s_and_b64 s[28:29], s[12:13], vcc
	v_mov_b32_e32 v191, 0xff800000
	v_mov_b32_e32 v190, 0xff800000
	s_and_saveexec_b64 s[12:13], s[28:29]
	s_cbranch_execz .LBB0_764
	v_add_u32_e32 v190, 0x1c0a8, v92
	ds_read_b32 v190, v190
.LBB0_764:
	s_or_b64 exec, exec, s[12:13]
	v_add_u32_e32 v214, 43, v95
	v_subrev_u32_e32 v215, 21, v93
	v_cmp_gt_u32_e32 vcc, s37, v214
	s_and_b64 s[12:13], s[10:11], vcc
	v_cmp_gt_i32_e32 vcc, s20, v215
	s_and_b64 s[28:29], s[12:13], vcc
	s_and_saveexec_b64 s[12:13], s[28:29]
	s_cbranch_execz .LBB0_766
	v_add_u32_e32 v191, 0x1c0ac, v92
	ds_read_b32 v191, v191
.LBB0_766:
	s_or_b64 exec, exec, s[12:13]
	v_add_u32_e32 v216, 48, v95
	v_add_u32_e32 v217, -16, v93
	v_cmp_gt_u32_e32 vcc, s37, v216
	s_and_b64 s[12:13], s[10:11], vcc
	v_cmp_gt_i32_e32 vcc, s20, v217
	s_and_b64 s[28:29], s[12:13], vcc
	v_mov_b32_e32 v193, 0xff800000
	v_mov_b32_e32 v192, 0xff800000
	s_and_saveexec_b64 s[12:13], s[28:29]
	s_cbranch_execz .LBB0_768
	v_add_u32_e32 v192, 0x1c0c0, v92
	ds_read_b32 v192, v192
.LBB0_768:
	s_or_b64 exec, exec, s[12:13]
	v_add_u32_e32 v218, 49, v95
	v_add_u32_e32 v219, -15, v93
	v_cmp_gt_u32_e32 vcc, s37, v218
	s_and_b64 s[12:13], s[10:11], vcc
	v_cmp_gt_i32_e32 vcc, s20, v219
	s_and_b64 s[28:29], s[12:13], vcc
	s_and_saveexec_b64 s[12:13], s[28:29]
	s_cbranch_execz .LBB0_770
	v_add_u32_e32 v193, 0x1c0c4, v92
	ds_read_b32 v193, v193
.LBB0_770:
	s_or_b64 exec, exec, s[12:13]
	v_add_u32_e32 v220, 50, v95
	v_add_u32_e32 v221, -14, v93
	v_cmp_gt_u32_e32 vcc, s37, v220
	s_and_b64 s[12:13], s[10:11], vcc
	v_cmp_gt_i32_e32 vcc, s20, v221
	s_and_b64 s[28:29], s[12:13], vcc
	v_mov_b32_e32 v195, 0xff800000
	v_mov_b32_e32 v194, 0xff800000
	s_and_saveexec_b64 s[12:13], s[28:29]
	s_cbranch_execz .LBB0_772
	v_add_u32_e32 v194, 0x1c0c8, v92
	ds_read_b32 v194, v194
.LBB0_772:
	s_or_b64 exec, exec, s[12:13]
	v_add_u32_e32 v222, 51, v95
	v_add_u32_e32 v223, -13, v93
	v_cmp_gt_u32_e32 vcc, s37, v222
	s_and_b64 s[12:13], s[10:11], vcc
	v_cmp_gt_i32_e32 vcc, s20, v223
	s_and_b64 s[28:29], s[12:13], vcc
	s_and_saveexec_b64 s[12:13], s[28:29]
	s_cbranch_execz .LBB0_774
	v_add_u32_e32 v195, 0x1c0cc, v92
	ds_read_b32 v195, v195
.LBB0_774:
	s_or_b64 exec, exec, s[12:13]
	v_add_u32_e32 v224, 56, v95
	v_add_u32_e32 v225, -8, v93
	v_cmp_gt_u32_e32 vcc, s37, v224
	s_and_b64 s[12:13], s[10:11], vcc
	v_cmp_gt_i32_e32 vcc, s20, v225
	s_and_b64 s[28:29], s[12:13], vcc
	v_mov_b32_e32 v197, 0xff800000
	v_mov_b32_e32 v196, 0xff800000
	s_and_saveexec_b64 s[12:13], s[28:29]
	s_cbranch_execz .LBB0_776
	v_add_u32_e32 v196, 0x1c0e0, v92
	ds_read_b32 v196, v196
.LBB0_776:
	s_or_b64 exec, exec, s[12:13]
	v_add_u32_e32 v226, 57, v95
	v_add_u32_e32 v227, -7, v93
	v_cmp_gt_u32_e32 vcc, s37, v226
	s_and_b64 s[12:13], s[10:11], vcc
	v_cmp_gt_i32_e32 vcc, s20, v227
	s_and_b64 s[28:29], s[12:13], vcc
	s_and_saveexec_b64 s[12:13], s[28:29]
	s_cbranch_execz .LBB0_778
	v_add_u32_e32 v197, 0x1c0e4, v92
	ds_read_b32 v197, v197
.LBB0_778:
	s_or_b64 exec, exec, s[12:13]
	v_add_u32_e32 v228, 58, v95
	v_add_u32_e32 v229, -6, v93
	v_cmp_gt_u32_e32 vcc, s37, v228
	s_and_b64 s[12:13], s[10:11], vcc
	v_cmp_gt_i32_e32 vcc, s20, v229
	s_and_b64 s[28:29], s[12:13], vcc
	v_mov_b32_e32 v199, 0xff800000
	v_mov_b32_e32 v198, 0xff800000
	s_and_saveexec_b64 s[12:13], s[28:29]
	s_cbranch_execz .LBB0_780
	v_add_u32_e32 v198, 0x1c0e8, v92
	ds_read_b32 v198, v198
.LBB0_780:
	s_or_b64 exec, exec, s[12:13]
	v_add_u32_e32 v200, 59, v95
	v_add_u32_e32 v201, -5, v93
	v_cmp_gt_u32_e32 vcc, s37, v200
	s_and_b64 s[10:11], s[10:11], vcc
	v_cmp_gt_i32_e32 vcc, s20, v201
	s_and_b64 s[12:13], s[10:11], vcc
	s_and_saveexec_b64 s[10:11], s[12:13]
	s_cbranch_execz .LBB0_782
	v_add_u32_e32 v199, 0x1c0ec, v92
	ds_read_b32 v199, v199
